# P0 work rebalancing: the 192 w_in conversion tiles moved from workgroups 0-191 to 32-223 (workgroups 0-31 alone run a fifth row-loop iteration)
# speedup vs baseline: 1.0066x; 1.0066x over previous
.LBB0_5:
	s_or_b64 exec, exec, s[0:1]
	s_sub_i32 s4, s59, 32
	s_cmpk_gt_u32 s4, 0xbf
	s_cbranch_scc1 .LBB0_8
	s_add_u32 s0, s80, 0xd0
	s_addc_u32 s1, s81, 0
	v_mov_b32_e32 v3, 0
	s_movk_i32 s2, 0x3040
	s_movk_i32 s3, 0x104
